# attention loops: row-sum chains no longer start with a +0 add (16 VALU ops removed per loop iteration set)
# speedup vs baseline: 1.0390x; 1.0074x over previous
.LBB0_134:
	v_exp_f32_e32 v228, v96
	v_exp_f32_e32 v112, v112
	v_exp_f32_e32 v96, v113
	v_exp_f32_e32 v113, v97
	v_exp_f32_e32 v233, v98
	v_exp_f32_e32 v114, v114
	v_exp_f32_e32 v98, v115
	v_add_f32_e32 v229, v113, v228
	v_exp_f32_e32 v115, v99
	v_exp_f32_e32 v116, v116
	v_add_f32_e32 v97, v96, v112
	v_add_f32_e32 v99, v233, v229
	v_exp_f32_e32 v229, v100
	v_exp_f32_e32 v100, v117
	v_add_f32_e32 v97, v114, v97
	v_exp_f32_e32 v117, v101
	v_exp_f32_e32 v101, v118
	v_add_f32_e32 v97, v98, v97
	v_exp_f32_e32 v118, v102
	v_exp_f32_e32 v102, v119
	v_add_f32_e32 v99, v115, v99
	v_add_f32_e32 v97, v116, v97
	v_exp_f32_e32 v103, v103
	v_exp_f32_e32 v119, v120
	v_add_f32_e32 v99, v229, v99
	v_add_f32_e32 v97, v100, v97
	v_exp_f32_e32 v120, v104
	v_exp_f32_e32 v104, v121
	v_add_f32_e32 v99, v117, v99
	v_add_f32_e32 v97, v101, v97
	v_exp_f32_e32 v121, v105
	v_exp_f32_e32 v105, v122
	v_add_f32_e32 v99, v118, v99
	v_add_f32_e32 v97, v102, v97
	v_exp_f32_e32 v122, v106
	v_exp_f32_e32 v106, v123
	v_add_f32_e32 v99, v103, v99
	v_add_f32_e32 v97, v119, v97
	v_exp_f32_e32 v123, v107
	v_exp_f32_e32 v107, v124
	v_add_f32_e32 v99, v120, v99
	v_add_f32_e32 v97, v104, v97
	v_exp_f32_e32 v124, v108
	v_exp_f32_e32 v108, v125
	v_add_f32_e32 v99, v121, v99
	v_add_f32_e32 v97, v105, v97
	v_exp_f32_e32 v125, v109
	v_exp_f32_e32 v109, v126
	v_exp_f32_e32 v126, v110
	v_exp_f32_e32 v110, v127
	v_add_f32_e32 v99, v122, v99
	v_add_f32_e32 v97, v106, v97
	v_add_f32_e32 v99, v123, v99
	v_add_f32_e32 v97, v107, v97
	v_exp_f32_e32 v111, v111
	v_add_f32_e32 v99, v124, v99
	v_add_f32_e32 v97, v108, v97
	v_cvt_pk_bf16_f32 v105, v105, v106
	v_cvt_pk_bf16_f32 v106, v107, v108
	v_cvt_pk_bf16_f32 v108, v120, v121
	v_exp_f32_e32 v120, v80
	v_exp_f32_e32 v121, v64
	v_add_f32_e32 v99, v125, v99
	v_add_f32_e32 v97, v109, v97
	v_cvt_pk_bf16_f32 v107, v109, v110
	v_cvt_pk_bf16_f32 v109, v122, v123
	v_exp_f32_e32 v122, v81
	v_exp_f32_e32 v123, v65
	v_add_f32_e32 v99, v126, v99
	v_add_f32_e32 v97, v110, v97
	v_cvt_pk_bf16_f32 v110, v124, v125
	v_exp_f32_e32 v124, v82
	v_exp_f32_e32 v125, v66
	v_add_f32_e32 v99, v111, v99
	v_cvt_pk_bf16_f32 v111, v126, v111
	v_exp_f32_e32 v66, v83
	v_exp_f32_e32 v126, v67
	v_exp_f32_e32 v81, v84
	v_exp_f32_e32 v80, v68
	v_add_f32_e32 v64, v122, v120
	v_add_f32_e32 v65, v123, v121
	v_exp_f32_e32 v83, v85
	v_exp_f32_e32 v82, v69
	v_add_f32_e32 v64, v124, v64
	v_add_f32_e32 v67, v125, v65
	v_exp_f32_e32 v85, v86
	v_exp_f32_e32 v84, v70
	v_add_f32_e32 v97, v99, v97
	v_add_f32_e32 v65, v66, v64
	v_add_f32_e32 v64, v126, v67
	v_exp_f32_e32 v87, v87
	v_exp_f32_e32 v86, v71
	v_add_f32_e32 v222, v222, v97
	v_cvt_pk_bf16_f32 v96, v112, v96
	v_cvt_pk_bf16_f32 v97, v114, v98
	v_cvt_pk_bf16_f32 v98, v116, v100
	v_cvt_pk_bf16_f32 v100, v228, v113
	v_exp_f32_e32 v113, v88
	v_exp_f32_e32 v112, v72
	v_add_f32_e32 v64, v80, v64
	v_add_f32_e32 v65, v81, v65
	v_exp_f32_e32 v89, v89
	v_exp_f32_e32 v88, v73
	v_add_f32_e32 v64, v82, v64
	v_add_f32_e32 v65, v83, v65
	v_cvt_pk_bf16_f32 v99, v101, v102
	v_cvt_pk_bf16_f32 v101, v233, v115
	v_exp_f32_e32 v115, v90
	v_exp_f32_e32 v114, v74
	v_add_f32_e32 v64, v84, v64
	v_add_f32_e32 v65, v85, v65
	v_exp_f32_e32 v91, v91
	v_exp_f32_e32 v90, v75
	v_add_f32_e32 v64, v86, v64
	v_add_f32_e32 v65, v87, v65
	v_cvt_pk_bf16_f32 v102, v229, v117
	v_exp_f32_e32 v117, v92
	v_exp_f32_e32 v116, v76
	v_add_f32_e32 v64, v112, v64
	v_add_f32_e32 v65, v113, v65
	v_exp_f32_e32 v93, v93
	v_exp_f32_e32 v92, v77
	v_add_f32_e32 v64, v88, v64
	v_add_f32_e32 v65, v89, v65
	v_cvt_pk_bf16_f32 v103, v118, v103
	v_cvt_pk_bf16_f32 v104, v119, v104
	v_exp_f32_e32 v119, v94
	v_exp_f32_e32 v118, v78
	v_add_f32_e32 v64, v114, v64
	v_add_f32_e32 v65, v115, v65
	v_exp_f32_e32 v95, v95
	v_exp_f32_e32 v94, v79
	v_add_f32_e32 v64, v90, v64
	v_add_f32_e32 v65, v91, v65
	v_cvt_pk_bf16_f32 v67, v85, v87
	v_add_f32_e32 v64, v116, v64
	v_add_f32_e32 v65, v117, v65
	v_cvt_pk_bf16_f32 v68, v121, v123
	v_add_f32_e32 v64, v92, v64
	v_add_f32_e32 v65, v93, v65
	v_cvt_pk_bf16_f32 v69, v125, v126
	v_add_f32_e32 v64, v118, v64
	v_add_f32_e32 v65, v119, v65
	v_cvt_pk_bf16_f32 v70, v80, v82
	v_add_f32_e32 v64, v94, v64
	v_add_f32_e32 v65, v95, v65
	v_cvt_pk_bf16_f32 v71, v84, v86
	v_add_f32_e32 v64, v64, v65
	v_add_f32_e32 v227, v227, v64
	v_cvt_pk_bf16_f32 v64, v120, v122
	v_cvt_pk_bf16_f32 v65, v124, v66
	v_cvt_pk_bf16_f32 v66, v81, v83
	v_cvt_pk_bf16_f32 v72, v113, v89
	v_cvt_pk_bf16_f32 v73, v115, v91
	v_cvt_pk_bf16_f32 v74, v117, v93
	v_cvt_pk_bf16_f32 v75, v119, v95
	v_cvt_pk_bf16_f32 v76, v112, v88
	v_cvt_pk_bf16_f32 v77, v114, v90
	v_cvt_pk_bf16_f32 v78, v116, v92
	v_cvt_pk_bf16_f32 v79, v118, v94
	s_waitcnt lgkmcnt(0)
	v_mfma_f32_32x32x16_bf16 v[48:63], v[188:191], v[96:99], v[48:63]
	s_waitcnt vmcnt(0)
	s_add_i32 s2, s13, s10
	s_addk_i32 s45, 0x4000
	s_cmpk_lg_i32 s2, 0x83
	s_waitcnt vmcnt(0)
	s_barrier
	v_mfma_f32_32x32x16_bf16 v[32:47], v[184:187], v[96:99], v[32:47]
	v_mfma_f32_32x32x16_bf16 v[16:31], v[188:191], v[64:67], v[16:31]
	v_mfma_f32_32x32x16_bf16 v[0:15], v[184:187], v[64:67], v[0:15]
	v_mfma_f32_32x32x16_bf16 v[48:63], v[180:183], v[104:107], v[48:63]
	v_mfma_f32_32x32x16_bf16 v[32:47], v[176:179], v[104:107], v[32:47]
	v_mfma_f32_32x32x16_bf16 v[16:31], v[180:183], v[72:75], v[16:31]
	v_mfma_f32_32x32x16_bf16 v[0:15], v[176:179], v[72:75], v[0:15]
	v_mfma_f32_32x32x16_bf16 v[48:63], v[172:175], v[100:103], v[48:63]
	v_mfma_f32_32x32x16_bf16 v[32:47], v[168:171], v[100:103], v[32:47]
	v_mfma_f32_32x32x16_bf16 v[16:31], v[172:175], v[68:71], v[16:31]
	v_mfma_f32_32x32x16_bf16 v[0:15], v[168:171], v[68:71], v[0:15]
	v_mfma_f32_32x32x16_bf16 v[48:63], v[164:167], v[108:111], v[48:63]
	v_mfma_f32_32x32x16_bf16 v[32:47], v[160:163], v[108:111], v[32:47]
	v_mfma_f32_32x32x16_bf16 v[16:31], v[164:167], v[76:79], v[16:31]
	v_mfma_f32_32x32x16_bf16 v[0:15], v[160:163], v[76:79], v[0:15]
	s_cbranch_scc0 .LBB0_147

.LBB0_171:
	v_add_f32_e32 v119, v121, v119
	v_add_f32_e32 v120, v122, v120
	v_add_f32_e32 v119, v123, v119
	v_add_f32_e32 v120, v125, v120
	v_add_f32_e32 v119, v126, v119
	v_add_f32_e32 v120, v127, v120
	v_add_f32_e32 v119, v130, v119
	v_exp_f32_e32 v125, v80
	v_exp_f32_e32 v130, v64
	v_add_f32_e32 v120, v131, v120
	v_add_f32_e32 v119, v132, v119
	v_exp_f32_e32 v131, v81
	v_exp_f32_e32 v132, v65
	v_add_f32_e32 v120, v133, v120
	v_add_f32_e32 v119, v134, v119
	v_exp_f32_e32 v133, v82
	v_exp_f32_e32 v134, v66
	v_add_f32_e32 v120, v135, v120
	v_add_f32_e32 v119, v140, v119
	v_exp_f32_e32 v135, v83
	v_exp_f32_e32 v140, v67
	v_add_f32_e32 v120, v141, v120
	v_add_f32_e32 v119, v142, v119
	v_add_f32_e32 v120, v143, v120
	v_add_f32_e32 v64, v131, v125
	v_add_f32_e32 v65, v132, v130
	v_add_f32_e32 v119, v144, v119
	v_add_f32_e32 v120, v145, v120
	v_add_f32_e32 v64, v133, v64
	v_add_f32_e32 v66, v134, v65
	v_add_f32_e32 v119, v146, v119
	v_add_f32_e32 v120, v147, v120
	v_add_f32_e32 v65, v135, v64
	v_add_f32_e32 v64, v140, v66
	v_exp_f32_e32 v67, v84
	v_exp_f32_e32 v66, v68
	v_add_f32_e32 v119, v148, v119
	v_add_f32_e32 v120, v149, v120
	v_exp_f32_e32 v81, v85
	v_exp_f32_e32 v80, v69
	v_add_f32_e32 v119, v150, v119
	v_add_f32_e32 v120, v151, v120
	v_exp_f32_e32 v83, v86
	v_exp_f32_e32 v82, v70
	v_add_f32_e32 v119, v152, v119
	v_add_f32_e32 v120, v153, v120
	v_exp_f32_e32 v85, v87
	v_exp_f32_e32 v84, v71
	v_add_f32_e32 v119, v154, v119
	v_add_f32_e32 v120, v155, v120
	v_exp_f32_e32 v87, v88
	v_exp_f32_e32 v86, v72
	v_add_f32_e32 v64, v66, v64
	v_add_f32_e32 v65, v67, v65
	v_add_f32_e32 v119, v156, v119
	v_add_f32_e32 v120, v157, v120
	v_exp_f32_e32 v89, v89
	v_exp_f32_e32 v88, v73
	v_add_f32_e32 v64, v80, v64
	v_add_f32_e32 v65, v81, v65
	v_add_f32_e32 v119, v120, v119
	v_exp_f32_e32 v121, v90
	v_exp_f32_e32 v120, v74
	v_add_f32_e32 v64, v82, v64
	v_add_f32_e32 v65, v83, v65
	v_exp_f32_e32 v91, v91
	v_exp_f32_e32 v90, v75
	v_add_f32_e32 v64, v84, v64
	v_add_f32_e32 v65, v85, v65
	v_exp_f32_e32 v123, v92
	v_exp_f32_e32 v122, v76
	v_add_f32_e32 v64, v86, v64
	v_add_f32_e32 v65, v87, v65
	v_exp_f32_e32 v93, v93
	v_exp_f32_e32 v92, v77
	v_add_f32_e32 v64, v88, v64
	v_add_f32_e32 v65, v89, v65
	v_exp_f32_e32 v127, v94
	v_exp_f32_e32 v126, v78
	v_add_f32_e32 v64, v120, v64
	v_add_f32_e32 v65, v121, v65
	v_exp_f32_e32 v95, v95
	v_exp_f32_e32 v94, v79
	v_add_f32_e32 v64, v90, v64
	v_add_f32_e32 v65, v91, v65
	v_cvt_pk_bf16_f32 v71, v82, v84
	v_add_f32_e32 v64, v122, v64
	v_add_f32_e32 v65, v123, v65
	v_cvt_pk_bf16_f32 v78, v67, v81
	v_add_f32_e32 v64, v92, v64
	v_add_f32_e32 v65, v93, v65
	v_cvt_pk_bf16_f32 v79, v83, v85
	v_add_f32_e32 v64, v126, v64
	v_add_f32_e32 v65, v127, v65
	v_cvt_pk_bf16_f32 v70, v66, v80
	v_add_f32_e32 v64, v94, v64
	v_add_f32_e32 v65, v95, v65
	v_cvt_pk_bf16_f32 v72, v87, v89
	v_add_f32_e32 v141, v64, v65
	v_cvt_pk_bf16_f32 v64, v86, v88
	v_add_u32_e32 v88, s8, v112
	v_add_u32_e32 v84, v88, v114
	ds_read_b128 v[80:83], v84 offset:4096
	ds_read_b128 v[84:87], v84 offset:8192
	v_cvt_pk_bf16_f32 v76, v125, v131
	v_cvt_pk_bf16_f32 v77, v133, v135
	v_cvt_pk_bf16_f32 v73, v121, v91
	v_cvt_pk_bf16_f32 v74, v123, v93
	s_waitcnt lgkmcnt(0)
	v_mfma_f32_32x32x16_bf16 v[0:15], v[80:83], v[76:79], v[0:15]
	v_add_u32_e32 v80, v88, v124
	v_cvt_pk_bf16_f32 v75, v127, v95
	v_cvt_pk_bf16_f32 v68, v130, v132
	v_cvt_pk_bf16_f32 v69, v134, v140
	v_cvt_pk_bf16_f32 v65, v120, v90
	v_cvt_pk_bf16_f32 v66, v122, v92
	v_cvt_pk_bf16_f32 v67, v126, v94
	v_mfma_f32_32x32x16_bf16 v[16:31], v[84:87], v[76:79], v[16:31]
	ds_read_b128 v[76:79], v80 offset:4096
	ds_read_b128 v[80:83], v80 offset:8192
	v_add_f32_e32 v119, v175, v119
	s_add_i32 s50, s50, 2
	v_add_f32_e32 v175, v141, v119
	s_cmp_lt_u32 s50, s11
	s_waitcnt lgkmcnt(0)
	v_mfma_f32_32x32x16_bf16 v[0:15], v[76:79], v[72:75], v[0:15]
	v_add_u32_e32 v76, v88, v128
	v_mfma_f32_32x32x16_bf16 v[16:31], v[80:83], v[72:75], v[16:31]
	ds_read_b128 v[72:75], v76 offset:4096
	ds_read_b128 v[76:79], v76 offset:8192
	s_waitcnt lgkmcnt(0)
	v_mfma_f32_32x32x16_bf16 v[0:15], v[72:75], v[68:71], v[0:15]
	v_add_u32_e32 v72, v88, v129
	v_mfma_f32_32x32x16_bf16 v[16:31], v[76:79], v[68:71], v[16:31]
	ds_read_b128 v[68:71], v72 offset:4096
	ds_read_b128 v[72:75], v72 offset:8192
	s_waitcnt vmcnt(0)
	s_waitcnt vmcnt(0) lgkmcnt(0)
	s_barrier
	v_mfma_f32_32x32x16_bf16 v[0:15], v[68:71], v[64:67], v[0:15]
	v_mfma_f32_32x32x16_bf16 v[16:31], v[72:75], v[64:67], v[16:31]
	s_cbranch_scc0 .LBB0_174
	s_mov_b32 s2, s12
	s_mov_b32 s12, s51
	s_branch .LBB0_160

.LBB0_202:
	v_add_f32_e32 v150, v152, v150
	v_add_f32_e32 v151, v153, v151
	v_add_f32_e32 v150, v154, v150
	v_add_f32_e32 v151, v155, v151
	v_add_f32_e32 v150, v156, v150
	v_add_f32_e32 v151, v157, v151
	v_add_f32_e32 v150, v158, v150
	v_add_f32_e32 v151, v159, v151
	v_add_f32_e32 v150, v160, v150
	v_add_f32_e32 v151, v161, v151
	v_add_f32_e32 v150, v162, v150
	v_add_f32_e32 v151, v163, v151
	v_add_f32_e32 v150, v164, v150
	v_add_f32_e32 v151, v165, v151
	v_add_f32_e32 v150, v166, v150
	v_add_f32_e32 v151, v167, v151
	v_add_f32_e32 v150, v168, v150
	v_add_f32_e32 v151, v169, v151
	v_add_f32_e32 v150, v175, v150
	v_add_f32_e32 v151, v176, v151
	v_add_f32_e32 v150, v177, v150
	v_add_f32_e32 v151, v185, v151
	v_add_f32_e32 v150, v186, v150
	v_add_f32_e32 v151, v187, v151
	v_add_f32_e32 v150, v188, v150
	v_add_f32_e32 v151, v189, v151
	v_add_f32_e32 v150, v190, v150
	v_add_f32_e32 v151, v191, v151
	v_add_f32_e32 v150, v192, v150
	v_add_f32_e32 v151, v206, v151
	v_add_f32_e32 v150, v151, v150
	v_exp_f32_e32 v151, v112
	v_exp_f32_e32 v160, v96
	v_exp_f32_e32 v113, v113
	v_exp_f32_e32 v161, v97
	v_exp_f32_e32 v162, v114
	v_exp_f32_e32 v163, v98
	v_exp_f32_e32 v164, v115
	v_exp_f32_e32 v165, v99
	v_add_f32_e32 v96, v113, v151
	v_add_f32_e32 v97, v161, v160
	v_add_f32_e32 v96, v162, v96
	v_add_f32_e32 v98, v163, v97
	v_add_f32_e32 v97, v164, v96
	v_add_f32_e32 v96, v165, v98
	v_exp_f32_e32 v99, v116
	v_exp_f32_e32 v98, v100
	v_exp_f32_e32 v115, v117
	v_exp_f32_e32 v114, v101
	v_exp_f32_e32 v117, v118
	v_exp_f32_e32 v116, v102
	v_exp_f32_e32 v119, v119
	v_exp_f32_e32 v118, v103
	v_exp_f32_e32 v153, v120
	v_exp_f32_e32 v152, v104
	v_add_f32_e32 v96, v98, v96
	v_add_f32_e32 v97, v99, v97
	v_exp_f32_e32 v121, v121
	v_exp_f32_e32 v120, v105
	v_add_f32_e32 v96, v114, v96
	v_add_f32_e32 v97, v115, v97
	v_exp_f32_e32 v155, v122
	v_exp_f32_e32 v154, v106
	v_add_f32_e32 v96, v116, v96
	v_add_f32_e32 v97, v117, v97
	v_exp_f32_e32 v123, v123
	v_exp_f32_e32 v122, v107
	v_add_f32_e32 v96, v118, v96
	v_add_f32_e32 v97, v119, v97
	v_exp_f32_e32 v157, v124
	v_exp_f32_e32 v156, v108
	v_add_f32_e32 v96, v152, v96
	v_add_f32_e32 v97, v153, v97
	v_exp_f32_e32 v125, v125
	v_exp_f32_e32 v124, v109
	v_add_f32_e32 v96, v120, v96
	v_add_f32_e32 v97, v121, v97
	v_exp_f32_e32 v159, v126
	v_exp_f32_e32 v158, v110
	v_add_f32_e32 v96, v154, v96
	v_add_f32_e32 v97, v155, v97
	v_exp_f32_e32 v127, v127
	v_exp_f32_e32 v126, v111
	v_add_f32_e32 v96, v122, v96
	v_add_f32_e32 v97, v123, v97
	v_cvt_pk_bf16_f32 v108, v151, v113
	v_add_f32_e32 v96, v156, v96
	v_add_f32_e32 v97, v157, v97
	v_add_u32_e32 v113, s42, v179
	v_add_f32_e32 v96, v124, v96
	v_add_f32_e32 v97, v125, v97
	v_cvt_pk_bf16_f32 v103, v116, v118
	v_add_f32_e32 v96, v158, v96
	v_add_f32_e32 v97, v159, v97
	v_add_u32_e32 v118, v113, v180
	v_add_f32_e32 v96, v126, v96
	v_add_f32_e32 v97, v127, v97
	v_cvt_pk_bf16_f32 v110, v99, v115
	v_cvt_pk_bf16_f32 v111, v117, v119
	v_cvt_pk_bf16_f32 v102, v98, v114
	ds_read_b128 v[114:117], v118 offset:4096
	v_add_f32_e32 v112, v96, v97
	v_cvt_pk_bf16_f32 v104, v153, v121
	v_cvt_pk_bf16_f32 v96, v152, v120
	ds_read_b128 v[118:121], v118 offset:8192
	v_cvt_pk_bf16_f32 v109, v162, v164
	v_cvt_pk_bf16_f32 v105, v155, v123
	v_cvt_pk_bf16_f32 v106, v157, v125
	s_waitcnt lgkmcnt(0)
	v_mfma_f32_32x32x16_bf16 v[32:47], v[114:117], v[108:111], v[32:47]
	v_add_u32_e32 v114, v113, v181
	v_cvt_pk_bf16_f32 v107, v159, v127
	v_cvt_pk_bf16_f32 v100, v160, v161
	v_cvt_pk_bf16_f32 v101, v163, v165
	v_cvt_pk_bf16_f32 v97, v154, v122
	v_cvt_pk_bf16_f32 v98, v156, v124
	v_cvt_pk_bf16_f32 v99, v158, v126
	v_mfma_f32_32x32x16_bf16 v[48:63], v[118:121], v[108:111], v[48:63]
	ds_read_b128 v[108:111], v114 offset:4096
	ds_read_b128 v[114:117], v114 offset:8192
	v_add_f32_e32 v150, v184, v150
	s_add_i32 s17, s17, 2
	v_add_f32_e32 v184, v112, v150
	s_cmp_lt_u32 s17, s11
	s_waitcnt lgkmcnt(0)
	v_mfma_f32_32x32x16_bf16 v[32:47], v[108:111], v[104:107], v[32:47]
	v_add_u32_e32 v108, v113, v182
	v_mfma_f32_32x32x16_bf16 v[48:63], v[114:117], v[104:107], v[48:63]
	ds_read_b128 v[104:107], v108 offset:4096
	ds_read_b128 v[108:111], v108 offset:8192
	s_waitcnt lgkmcnt(0)
	v_mfma_f32_32x32x16_bf16 v[32:47], v[104:107], v[100:103], v[32:47]
	v_add_u32_e32 v104, v113, v183
	v_mfma_f32_32x32x16_bf16 v[48:63], v[108:111], v[100:103], v[48:63]
	ds_read_b128 v[100:103], v104 offset:4096
	ds_read_b128 v[104:107], v104 offset:8192
	s_waitcnt vmcnt(0)
	s_waitcnt vmcnt(0) lgkmcnt(0)
	s_barrier
	v_mfma_f32_32x32x16_bf16 v[32:47], v[100:103], v[96:99], v[32:47]
	v_mfma_f32_32x32x16_bf16 v[48:63], v[104:107], v[96:99], v[48:63]
	s_cbranch_scc0 .LBB0_205
	s_mov_b32 s2, s12
	s_mov_b32 s12, s10
	s_branch .LBB0_191

.LBB0_234:
	v_add_f32_e32 v143, v151, v143
	v_add_f32_e32 v150, v152, v150
	v_add_f32_e32 v143, v153, v143
	v_add_f32_e32 v150, v172, v150
	v_add_f32_e32 v143, v154, v143
	v_add_f32_e32 v150, v170, v150
	v_add_f32_e32 v143, v155, v143
	v_add_f32_e32 v150, v169, v150
	v_add_f32_e32 v143, v156, v143
	v_add_f32_e32 v150, v168, v150
	v_add_f32_e32 v143, v159, v143
	v_add_f32_e32 v150, v167, v150
	v_add_f32_e32 v143, v158, v143
	v_add_f32_e32 v150, v173, v150
	v_add_f32_e32 v143, v157, v143
	v_add_f32_e32 v150, v171, v150
	v_add_f32_e32 v143, v165, v143
	v_add_f32_e32 v150, v179, v150
	v_add_f32_e32 v143, v163, v143
	v_add_f32_e32 v150, v177, v150
	v_add_f32_e32 v143, v162, v143
	v_add_f32_e32 v150, v176, v150
	v_add_f32_e32 v143, v161, v143
	v_add_f32_e32 v150, v175, v150
	v_add_f32_e32 v143, v160, v143
	v_add_f32_e32 v150, v174, v150
	v_add_f32_e32 v143, v166, v143
	v_add_f32_e32 v150, v180, v150
	v_add_f32_e32 v143, v164, v143
	v_add_f32_e32 v150, v178, v150
	v_add_f32_e32 v143, v150, v143
	v_exp_f32_e32 v151, v80
	v_exp_f32_e32 v150, v64
	v_exp_f32_e32 v153, v81
	v_exp_f32_e32 v152, v65
	v_exp_f32_e32 v65, v82
	v_exp_f32_e32 v64, v66
	v_exp_f32_e32 v83, v83
	v_exp_f32_e32 v82, v67
	v_exp_f32_e32 v155, v84
	v_exp_f32_e32 v154, v68
	v_add_f32_e32 v66, v152, v150
	v_add_f32_e32 v67, v153, v151
	v_exp_f32_e32 v85, v85
	v_exp_f32_e32 v84, v69
	v_add_f32_e32 v66, v64, v66
	v_add_f32_e32 v67, v65, v67
	v_exp_f32_e32 v157, v86
	v_exp_f32_e32 v156, v70
	v_add_f32_e32 v66, v82, v66
	v_add_f32_e32 v67, v83, v67
	v_exp_f32_e32 v87, v87
	v_exp_f32_e32 v86, v71
	v_exp_f32_e32 v159, v88
	v_exp_f32_e32 v158, v72
	v_add_f32_e32 v66, v154, v66
	v_add_f32_e32 v67, v155, v67
	v_exp_f32_e32 v89, v89
	v_exp_f32_e32 v88, v73
	v_add_f32_e32 v66, v84, v66
	v_add_f32_e32 v67, v85, v67
	v_add_u32_e32 v81, s8, v139
	v_add_f32_e32 v66, v156, v66
	v_add_f32_e32 v67, v157, v67
	v_cvt_pk_bf16_f32 v71, v156, v86
	v_add_f32_e32 v66, v86, v66
	v_add_f32_e32 v67, v87, v67
	v_add_u32_e32 v86, v81, v148
	v_exp_f32_e32 v163, v92
	v_exp_f32_e32 v92, v77
	v_exp_f32_e32 v164, v78
	v_add_f32_e32 v66, v158, v66
	v_add_f32_e32 v67, v159, v67
	v_cvt_pk_bf16_f32 v77, v65, v83
	v_cvt_pk_bf16_f32 v78, v155, v85
	v_cvt_pk_bf16_f32 v69, v64, v82
	v_cvt_pk_bf16_f32 v70, v154, v84
	ds_read_b128 v[82:85], v86 offset:12288
	v_exp_f32_e32 v165, v94
	v_exp_f32_e32 v94, v79
	v_add_f32_e32 v66, v88, v66
	v_add_f32_e32 v67, v89, v67
	v_cvt_pk_bf16_f32 v79, v157, v87
	v_cvt_pk_bf16_f32 v72, v159, v89
	v_cvt_pk_bf16_f32 v64, v158, v88
	ds_read_b128 v[86:89], v86 offset:16384
	v_exp_f32_e32 v162, v76
	v_cvt_pk_bf16_f32 v76, v151, v153
	v_exp_f32_e32 v161, v90
	v_exp_f32_e32 v91, v91
	s_waitcnt lgkmcnt(0)
	v_mfma_f32_32x32x16_bf16 v[16:31], v[82:85], v[76:79], v[16:31]
	v_add_u32_e32 v82, v81, v147
	v_exp_f32_e32 v93, v93
	v_exp_f32_e32 v95, v95
	v_exp_f32_e32 v160, v74
	v_exp_f32_e32 v90, v75
	v_cvt_pk_bf16_f32 v73, v161, v91
	v_cvt_pk_bf16_f32 v74, v163, v93
	v_mfma_f32_32x32x16_bf16 v[0:15], v[86:89], v[76:79], v[0:15]
	ds_read_b128 v[76:79], v82 offset:12288
	ds_read_b128 v[82:85], v82 offset:16384
	v_cvt_pk_bf16_f32 v75, v165, v95
	v_cvt_pk_bf16_f32 v68, v150, v152
	v_add_f32_e64 v66, v160, v66
	v_add_f32_e64 v67, v161, v67
	v_cvt_pk_bf16_f32 v65, v160, v90
	v_add_f32_e32 v66, v90, v66
	v_add_f32_e32 v67, v91, v67
	s_waitcnt lgkmcnt(0)
	v_mfma_f32_32x32x16_bf16 v[16:31], v[76:79], v[72:75], v[16:31]
	v_add_u32_e32 v76, v81, v146
	v_add_f32_e64 v66, v162, v66
	v_add_f32_e64 v67, v163, v67
	v_add_f32_e32 v143, v149, v143
	v_add_f32_e64 v66, v92, v66
	v_add_f32_e64 v67, v93, v67
	s_cmp_lt_u32 s70, s10
	v_add_f32_e32 v66, v164, v66
	v_add_f32_e32 v67, v165, v67
	v_mfma_f32_32x32x16_bf16 v[0:15], v[82:85], v[72:75], v[0:15]
	ds_read_b128 v[72:75], v76 offset:12288
	ds_read_b128 v[76:79], v76 offset:16384
	v_add_f32_e64 v66, v94, v66
	v_add_f32_e64 v67, v95, v67
	v_add_f32_e32 v80, v66, v67
	v_cvt_pk_bf16_f32 v66, v162, v92
	v_cvt_pk_bf16_f32 v67, v164, v94
	s_waitcnt lgkmcnt(0)
	v_mfma_f32_32x32x16_bf16 v[16:31], v[72:75], v[68:71], v[16:31]
	v_add_u32_e32 v72, v81, v145
	v_add_f32_e32 v149, v80, v143
	v_mfma_f32_32x32x16_bf16 v[0:15], v[76:79], v[68:71], v[0:15]
	ds_read_b128 v[68:71], v72 offset:12288
	ds_read_b128 v[72:75], v72 offset:16384
	s_waitcnt vmcnt(0)
	s_waitcnt vmcnt(0) lgkmcnt(0)
	s_barrier
	v_mfma_f32_32x32x16_bf16 v[16:31], v[68:71], v[64:67], v[16:31]
	v_mfma_f32_32x32x16_bf16 v[0:15], v[72:75], v[64:67], v[0:15]
	s_cbranch_scc0 .LBB0_237
	s_mov_b32 s2, s17
	s_mov_b32 s17, s18
	s_mov_b32 s19, s70
	s_branch .LBB0_223
